# final stack with the P2 w_in conversion rebalanced: the 512 tenth items of workgroups 64..255 go one each to the waves of workgroups 0..63 after their sample piece (9 items per wave everywhere else)
# speedup vs baseline: 1.0021x; 1.0021x over previous
; #define LAS __attribute__((address_space(3)))
;     ...
;     { float wv[32];
;       const float* wp = W + (size_t)(k0 + (lane >> 5)) * ldw + n0 + (lane & 31);
; #pragma unroll
;       for (int i = 0; i < 32; ++i) wv[i] = wp[(size_t)(2 * i) * ldw];
; #pragma unroll
;       for (int i = 0; i < 32; ++i) scr[(2 * i + (lane >> 5)) * 33 + (lane & 31)] = wv[i]; }
; template <bool LATE = false>
; __device__ __forceinline__ void transpose_tail(Frame& F, const Args& a, int bx, int lo, int first, int count) {
;     if (F.G != 256 || bx < lo) return;
;     LAS float* scr = (LAS float*)(F.lds + F.wave * 16384);
;     for (int j = (bx - lo) * NWAVES + F.wave; j < count; j += (F.G - lo) * NWAVES) { if (LATE) transpose_late(a, F, scr, first + j); else transpose_early(a, F, scr, first + j); }
.LBB0_200:
	s_cmpk_lg_i32 s96, 0x100
	s_cbranch_scc1 .LBB0_220
	s_load_dwordx2 s[42:43], s[0:1], 0x70
	s_add_u32 s44, s34, 0x4300000
	s_addc_u32 s45, s35, 0
	s_lshl_b32 s46, s2, 3
	s_add_i32 s46, s46, s97
	s_cmpk_lt_i32 s2, 0x40
	s_cbranch_scc1 .Ltr2_cls
	s_addk_i32 s46, 0xfe00
	s_movk_i32 s54, 0x3600
	s_branch .Ltr2_clsd
.Ltr2_cls:
	s_addk_i32 s46, 0x3600
	s_movk_i32 s54, 0x3800
.Ltr2_clsd:
	s_lshl_b32 s47, s97, 14
	v_mbcnt_lo_u32_b32 v2, -1, 0
	v_mbcnt_hi_u32_b32 v2, -1, v2
	v_lshrrev_b32_e32 v88, 3, v2
	v_and_b32_e32 v89, 7, v2
	v_mul_u32_u24_e32 v3, 0xe020, v88
	v_lshl_add_u32 v3, v89, 4, v3
	v_add_u32_e32 v4, 0x70100, v3
	v_add_u32_e32 v5, 0xe0200, v3
	v_add_u32_e32 v6, 0x150300, v3
	v_add_u32_e32 v7, 0x1c0400, v3
	v_add_u32_e32 v8, 0x230500, v3
	v_add_u32_e32 v9, 0x2a0600, v3
	v_add_u32_e32 v10, 0x310700, v3
	v_lshlrev_b32_e32 v11, 12, v88
	v_lshl_add_u32 v11, v89, 4, v11
	v_add_u32_e32 v12, 0x8000, v11
	v_add_u32_e32 v13, 0x10000, v11
	v_add_u32_e32 v14, 0x18000, v11
	v_mul_u32_u24_e32 v15, 132, v88
	v_lshl_add_u32 v15, v89, 4, v15
	v_add_u32_e32 v15, s47, v15
	v_add_u32_e32 v16, 1056, v15
	v_add_u32_e32 v17, 2112, v15
	v_add_u32_e32 v18, 3168, v15
	v_add_u32_e32 v19, 4224, v15
	v_add_u32_e32 v20, 5280, v15
	v_add_u32_e32 v21, 6336, v15
	v_add_u32_e32 v22, 7392, v15
	v_mul_u32_u24_e32 v23, 1056, v89
	v_lshl_add_u32 v23, v88, 2, v23
	v_add_u32_e32 v23, s47, v23
	s_waitcnt lgkmcnt(0)
	s_cmpk_lt_u32 s46, 0x1800
	s_cbranch_scc0 .Ltr2_b0
	s_lshr_b32 s57, s46, 6
	s_mul_i32 s57, s57, 171
	s_lshr_b32 s57, s57, 9
	s_mul_i32 s60, s57, 192
	s_sub_u32 s58, s46, s60
	s_mov_b32 s60, 0
	s_mov_b32 s61, 0
	s_branch .Ltr2_c0

;     ...
;     { float wv[32];
;       const float* wp = W + (size_t)(k0 + (lane >> 5)) * ldw + n0 + (lane & 31);
; #pragma unroll
;       for (int i = 0; i < 32; ++i) wv[i] = wp[(size_t)(2 * i) * ldw];
; #pragma unroll
;       for (int i = 0; i < 32; ++i) scr[(2 * i + (lane >> 5)) * 33 + (lane & 31)] = wv[i]; }
; template <bool LATE = false>
; __device__ __forceinline__ void transpose_tail(Frame& F, const Args& a, int bx, int lo, int first, int count) {
;     ...
;     for (int j = (bx - lo) * NWAVES + F.wave; j < count; j += (F.G - lo) * NWAVES) { if (LATE) transpose_late(a, F, scr, first + j); else transpose_early(a, F, scr, first + j); }
.Ltr2_A:
	ds_write2_b32 v15, v24, v25 offset1:1
	ds_write2_b32 v15, v26, v27 offset0:2 offset1:3
	ds_write2_b32 v16, v28, v29 offset1:1
	ds_write2_b32 v16, v30, v31 offset0:2 offset1:3
	ds_write2_b32 v17, v32, v33 offset1:1
	ds_write2_b32 v17, v34, v35 offset0:2 offset1:3
	ds_write2_b32 v18, v36, v37 offset1:1
	ds_write2_b32 v18, v38, v39 offset0:2 offset1:3
	ds_write2_b32 v19, v40, v41 offset1:1
	ds_write2_b32 v19, v42, v43 offset0:2 offset1:3
	ds_write2_b32 v20, v44, v45 offset1:1
	ds_write2_b32 v20, v46, v47 offset0:2 offset1:3
	ds_write2_b32 v21, v48, v49 offset1:1
	ds_write2_b32 v21, v50, v51 offset0:2 offset1:3
	ds_write2_b32 v22, v52, v53 offset1:1
	ds_write2_b32 v22, v54, v55 offset0:2 offset1:3
	s_mov_b64 s[62:63], s[50:51]
	s_add_i32 s46, s46, 0x600
	s_cmp_lt_u32 s46, s54
	s_cselect_b32 s59, 1, 0
	s_cbranch_scc0 .Ltr2_np_A
	s_cmpk_lt_u32 s46, 0x1800
	s_cbranch_scc0 .Ltr2_b1
	s_lshr_b32 s57, s46, 6
	s_mul_i32 s57, s57, 171
	s_lshr_b32 s57, s57, 9
	s_mul_i32 s60, s57, 192
	s_sub_u32 s58, s46, s60
	s_mov_b32 s60, 0
	s_mov_b32 s61, 0
	s_branch .Ltr2_c1

;     ...
;     { float wv[32];
;       const float* wp = W + (size_t)(k0 + (lane >> 5)) * ldw + n0 + (lane & 31);
; #pragma unroll
;       for (int i = 0; i < 32; ++i) wv[i] = wp[(size_t)(2 * i) * ldw];
; #pragma unroll
;       for (int i = 0; i < 32; ++i) scr[(2 * i + (lane >> 5)) * 33 + (lane & 31)] = wv[i]; }
; template <bool LATE = false>
; __device__ __forceinline__ void transpose_tail(Frame& F, const Args& a, int bx, int lo, int first, int count) {
;     ...
;     for (int j = (bx - lo) * NWAVES + F.wave; j < count; j += (F.G - lo) * NWAVES) { if (LATE) transpose_late(a, F, scr, first + j); else transpose_early(a, F, scr, first + j); }
.Ltr2_B:
	ds_write2_b32 v15, v56, v57 offset1:1
	ds_write2_b32 v15, v58, v59 offset0:2 offset1:3
	ds_write2_b32 v16, v60, v61 offset1:1
	ds_write2_b32 v16, v62, v63 offset0:2 offset1:3
	ds_write2_b32 v17, v64, v65 offset1:1
	ds_write2_b32 v17, v66, v67 offset0:2 offset1:3
	ds_write2_b32 v18, v68, v69 offset1:1
	ds_write2_b32 v18, v70, v71 offset0:2 offset1:3
	ds_write2_b32 v19, v72, v73 offset1:1
	ds_write2_b32 v19, v74, v75 offset0:2 offset1:3
	ds_write2_b32 v20, v76, v77 offset1:1
	ds_write2_b32 v20, v78, v79 offset0:2 offset1:3
	ds_write2_b32 v21, v80, v81 offset1:1
	ds_write2_b32 v21, v82, v83 offset0:2 offset1:3
	ds_write2_b32 v22, v84, v85 offset1:1
	ds_write2_b32 v22, v86, v87 offset0:2 offset1:3
	s_mov_b64 s[62:63], s[50:51]
	s_add_i32 s46, s46, 0x600
	s_cmp_lt_u32 s46, s54
	s_cselect_b32 s59, 1, 0
	s_cbranch_scc0 .Ltr2_np_B
	s_cmpk_lt_u32 s46, 0x1800
	s_cbranch_scc0 .Ltr2_b2
	s_lshr_b32 s57, s46, 6
	s_mul_i32 s57, s57, 171
	s_lshr_b32 s57, s57, 9
	s_mul_i32 s60, s57, 192
	s_sub_u32 s58, s46, s60
	s_mov_b32 s60, 0
	s_mov_b32 s61, 0
	s_branch .Ltr2_c2
